# grid barrier: waiters poll the top-level arrival counter directly (no generation word bumped by the last leader)
# speedup vs baseline: 1.0351x; 1.0085x over previous
.LBB0_113:
	s_or_b64 exec, exec, s[16:17]
	buffer_inv sc1
	v_cvt_f32_u32_e32 v5, v3
	s_waitcnt vmcnt(1)
	v_readfirstlane_b32 s2, v4
	v_sub_u32_e32 v4, 0, v3
	v_rcp_iflag_f32_e32 v5, v5
	v_add_u32_e32 v6, s2, v2
	v_mul_f32_e32 v5, 0x4f7ffffe, v5
	v_cvt_u32_f32_e32 v5, v5
	v_mul_lo_u32 v2, v4, v5
	v_mul_hi_u32 v2, v5, v2
	v_add_u32_e32 v2, v5, v2
	v_mul_hi_u32 v2, v6, v2
	v_mul_lo_u32 v4, v2, v3
	v_sub_u32_e32 v4, v6, v4
	v_add_u32_e32 v5, 1, v2
	v_cmp_ge_u32_e32 vcc, v4, v3
	s_nop 1
	v_cndmask_b32_e32 v2, v2, v5, vcc
	v_sub_u32_e32 v5, v4, v3
	v_cndmask_b32_e32 v4, v4, v5, vcc
	v_add_u32_e32 v5, 1, v2
	v_cmp_ge_u32_e32 vcc, v4, v3
	v_add_u32_e32 v4, 1, v6
	s_nop 0
	v_cndmask_b32_e32 v2, v2, v5, vcc
	v_mul_lo_u32 v5, v3, v2
	v_add_u32_e32 v3, v5, v3
	v_cmp_ne_u32_e32 vcc, v4, v3
	s_and_saveexec_b64 s[2:3], vcc
	s_xor_b64 s[10:11], exec, s[2:3]
	s_cbranch_execz .LBB0_127
	s_waitcnt lgkmcnt(0)
	v_add_u32_e32 v2, 1, v2
	v_mul_lo_u32 v2, v2, v1
	v_mov_b32_e32 v1, 0x3400
	global_load_dword v1, v1, s[60:61] sc1
	s_add_u32 s20, s60, 0x3400
	s_addc_u32 s21, s61, 0
	s_waitcnt vmcnt(0)
	v_cmp_lt_u32_e32 vcc, v1, v2
	s_and_saveexec_b64 s[16:17], vcc
	s_cbranch_execz .LBB0_126
	s_add_u32 s18, s88, 0xc67d200
	s_addc_u32 s19, s89, 0
	s_mov_b32 s2, 1
	s_mov_b64 s[22:23], 0
	v_mov_b32_e32 v1, 0
	s_branch .LBB0_117

.LBB0_121:
	global_load_dword v3, v1, s[20:21] sc1
	s_add_i32 s2, s2, 1
	s_mov_b64 s[28:29], -1
	s_waitcnt vmcnt(0)
	v_cmp_ge_u32_e32 vcc, v3, v2
	s_orn2_b64 s[26:27], vcc, exec
	s_branch .LBB0_116

.LBB0_130:
	s_or_b64 exec, exec, s[16:17]
	v_cvt_f32_u32_e32 v4, v1
	s_waitcnt vmcnt(0)
	v_readfirstlane_b32 s2, v3
	s_add_u32 s16, s88, 0xc680400
	s_addc_u32 s17, s89, 0
	v_rcp_iflag_f32_e32 v4, v4
	v_add_u32_e32 v2, s2, v2
	v_add_u32_e32 v5, 1, v2
	s_mov_b64 s[18:19], 0
	v_mul_f32_e32 v3, 0x4f7ffffe, v4
	v_cvt_u32_f32_e32 v3, v3
	v_sub_u32_e32 v4, 0, v1
	v_mul_lo_u32 v4, v4, v3
	v_mul_hi_u32 v4, v3, v4
	v_add_u32_e32 v3, v3, v4
	v_mul_hi_u32 v3, v2, v3
	v_mul_lo_u32 v4, v3, v1
	v_sub_u32_e32 v2, v2, v4
	v_add_u32_e32 v6, 1, v3
	v_cmp_ge_u32_e32 vcc, v2, v1
	v_sub_u32_e32 v4, v2, v1
	s_nop 0
	v_cndmask_b32_e32 v3, v3, v6, vcc
	v_cndmask_b32_e32 v2, v2, v4, vcc
	v_add_u32_e32 v4, 1, v3
	v_cmp_ge_u32_e32 vcc, v2, v1
	s_nop 1
	v_cndmask_b32_e32 v4, v3, v4, vcc
	v_mul_lo_u32 v2, v1, v4
	v_add_u32_e32 v1, v2, v1
	v_cmp_ne_u32_e32 vcc, v5, v1
	v_mov_b32_e32 v4, v1
	v_mov_b64_e32 v[2:3], s[16:17]
	s_and_saveexec_b64 s[10:11], vcc
	s_cbranch_execz .LBB0_142
	v_mov_b32_e32 v1, 0
	global_load_dword v2, v1, s[16:17] sc1
	s_mov_b64 s[22:23], 0
	s_waitcnt vmcnt(0)
	v_cmp_lt_u32_e32 vcc, v2, v4
	s_and_saveexec_b64 s[20:21], vcc
	s_cbranch_execz .LBB0_141
	s_add_u32 s18, s88, 0xc67d200
	s_addc_u32 s19, s89, 0
	s_mov_b32 s2, 1
	s_branch .LBB0_134

.LBB0_138:
	global_load_dword v2, v1, s[16:17] sc1
	s_add_i32 s2, s2, 1
	s_mov_b64 s[26:27], -1
	s_waitcnt vmcnt(0)
	v_cmp_ge_u32_e32 vcc, v2, v4
	s_orn2_b64 s[30:31], vcc, exec
	s_branch .LBB0_133

.LBB0_330:
	s_or_b64 exec, exec, s[10:11]
	buffer_inv sc1
	v_cvt_f32_u32_e32 v5, v3
	s_waitcnt vmcnt(1)
	v_readfirstlane_b32 s2, v4
	v_sub_u32_e32 v4, 0, v3
	v_rcp_iflag_f32_e32 v5, v5
	v_add_u32_e32 v6, s2, v2
	v_mul_f32_e32 v5, 0x4f7ffffe, v5
	v_cvt_u32_f32_e32 v5, v5
	v_mul_lo_u32 v2, v4, v5
	v_mul_hi_u32 v2, v5, v2
	v_add_u32_e32 v2, v5, v2
	v_mul_hi_u32 v2, v6, v2
	v_mul_lo_u32 v4, v2, v3
	v_sub_u32_e32 v4, v6, v4
	v_add_u32_e32 v5, 1, v2
	v_cmp_ge_u32_e32 vcc, v4, v3
	s_nop 1
	v_cndmask_b32_e32 v2, v2, v5, vcc
	v_sub_u32_e32 v5, v4, v3
	v_cndmask_b32_e32 v4, v4, v5, vcc
	v_add_u32_e32 v5, 1, v2
	v_cmp_ge_u32_e32 vcc, v4, v3
	v_add_u32_e32 v4, 1, v6
	s_nop 0
	v_cndmask_b32_e32 v2, v2, v5, vcc
	v_mul_lo_u32 v5, v3, v2
	v_add_u32_e32 v3, v5, v3
	v_cmp_ne_u32_e32 vcc, v4, v3
	s_and_saveexec_b64 s[2:3], vcc
	s_xor_b64 s[8:9], exec, s[2:3]
	s_cbranch_execz .LBB0_344
	s_waitcnt lgkmcnt(0)
	v_add_u32_e32 v2, 1, v2
	v_mul_lo_u32 v2, v2, v1
	v_mov_b32_e32 v1, 0x3400
	global_load_dword v1, v1, s[60:61] sc1
	s_add_u32 s14, s60, 0x3400
	s_addc_u32 s15, s61, 0
	s_waitcnt vmcnt(0)
	v_cmp_lt_u32_e32 vcc, v1, v2
	s_and_saveexec_b64 s[10:11], vcc
	s_cbranch_execz .LBB0_343
	s_add_u32 s12, s88, 0xc67d200
	s_addc_u32 s13, s89, 0
	s_mov_b32 s2, 1
	s_mov_b64 s[16:17], 0
	v_mov_b32_e32 v1, 0
	s_branch .LBB0_334

.LBB0_338:
	global_load_dword v3, v1, s[14:15] sc1
	s_add_i32 s2, s2, 1
	s_mov_b64 s[22:23], -1
	s_waitcnt vmcnt(0)
	v_cmp_ge_u32_e32 vcc, v3, v2
	s_orn2_b64 s[20:21], vcc, exec
	s_branch .LBB0_333

.LBB0_347:
	s_or_b64 exec, exec, s[10:11]
	v_cvt_f32_u32_e32 v4, v1
	s_waitcnt vmcnt(0)
	v_readfirstlane_b32 s2, v3
	s_add_u32 s10, s88, 0xc680400
	s_addc_u32 s11, s89, 0
	v_rcp_iflag_f32_e32 v4, v4
	v_add_u32_e32 v2, s2, v2
	v_add_u32_e32 v5, 1, v2
	s_mov_b64 s[12:13], 0
	v_mul_f32_e32 v3, 0x4f7ffffe, v4
	v_cvt_u32_f32_e32 v3, v3
	v_sub_u32_e32 v4, 0, v1
	v_mul_lo_u32 v4, v4, v3
	v_mul_hi_u32 v4, v3, v4
	v_add_u32_e32 v3, v3, v4
	v_mul_hi_u32 v3, v2, v3
	v_mul_lo_u32 v4, v3, v1
	v_sub_u32_e32 v2, v2, v4
	v_add_u32_e32 v6, 1, v3
	v_cmp_ge_u32_e32 vcc, v2, v1
	v_sub_u32_e32 v4, v2, v1
	s_nop 0
	v_cndmask_b32_e32 v3, v3, v6, vcc
	v_cndmask_b32_e32 v2, v2, v4, vcc
	v_add_u32_e32 v4, 1, v3
	v_cmp_ge_u32_e32 vcc, v2, v1
	s_nop 1
	v_cndmask_b32_e32 v4, v3, v4, vcc
	v_mul_lo_u32 v2, v1, v4
	v_add_u32_e32 v1, v2, v1
	v_cmp_ne_u32_e32 vcc, v5, v1
	v_mov_b32_e32 v4, v1
	v_mov_b64_e32 v[2:3], s[10:11]
	s_and_saveexec_b64 s[8:9], vcc
	s_cbranch_execz .LBB0_359
	v_mov_b32_e32 v1, 0
	global_load_dword v2, v1, s[10:11] sc1
	s_mov_b64 s[16:17], 0
	s_waitcnt vmcnt(0)
	v_cmp_lt_u32_e32 vcc, v2, v4
	s_and_saveexec_b64 s[14:15], vcc
	s_cbranch_execz .LBB0_358
	s_add_u32 s12, s88, 0xc67d200
	s_addc_u32 s13, s89, 0
	s_mov_b32 s2, 1
	s_branch .LBB0_351

.LBB0_355:
	global_load_dword v2, v1, s[10:11] sc1
	s_add_i32 s2, s2, 1
	s_mov_b64 s[20:21], -1
	s_waitcnt vmcnt(0)
	v_cmp_ge_u32_e32 vcc, v2, v4
	s_orn2_b64 s[24:25], vcc, exec
	s_branch .LBB0_350

.LBB0_600:
	s_or_b64 exec, exec, s[10:11]
	buffer_inv sc1
	v_cvt_f32_u32_e32 v6, v4
	s_waitcnt vmcnt(1)
	v_readfirstlane_b32 s2, v5
	v_sub_u32_e32 v5, 0, v4
	v_rcp_iflag_f32_e32 v6, v6
	v_add_u32_e32 v7, s2, v3
	v_mul_f32_e32 v6, 0x4f7ffffe, v6
	v_cvt_u32_f32_e32 v6, v6
	v_mul_lo_u32 v3, v5, v6
	v_mul_hi_u32 v3, v6, v3
	v_add_u32_e32 v3, v6, v3
	v_mul_hi_u32 v3, v7, v3
	v_mul_lo_u32 v5, v3, v4
	v_sub_u32_e32 v5, v7, v5
	v_add_u32_e32 v6, 1, v3
	v_cmp_ge_u32_e32 vcc, v5, v4
	s_nop 1
	v_cndmask_b32_e32 v3, v3, v6, vcc
	v_sub_u32_e32 v6, v5, v4
	v_cndmask_b32_e32 v5, v5, v6, vcc
	v_add_u32_e32 v6, 1, v3
	v_cmp_ge_u32_e32 vcc, v5, v4
	v_add_u32_e32 v5, 1, v7
	s_nop 0
	v_cndmask_b32_e32 v3, v3, v6, vcc
	v_mul_lo_u32 v6, v4, v3
	v_add_u32_e32 v4, v6, v4
	v_cmp_ne_u32_e32 vcc, v5, v4
	s_and_saveexec_b64 s[2:3], vcc
	s_xor_b64 s[8:9], exec, s[2:3]
	s_cbranch_execz .LBB0_614
	s_waitcnt lgkmcnt(0)
	v_add_u32_e32 v3, 1, v3
	v_mul_lo_u32 v3, v3, v2
	v_mov_b32_e32 v2, 0x3400
	global_load_dword v2, v2, s[60:61] sc1
	s_add_u32 s14, s60, 0x3400
	s_addc_u32 s15, s61, 0
	s_waitcnt vmcnt(0)
	v_cmp_lt_u32_e32 vcc, v2, v3
	s_and_saveexec_b64 s[10:11], vcc
	s_cbranch_execz .LBB0_613
	s_add_u32 s12, s88, 0xc67d200
	s_addc_u32 s13, s89, 0
	s_mov_b32 s2, 1
	s_mov_b64 s[16:17], 0
	v_mov_b32_e32 v2, 0
	s_branch .LBB0_604

.LBB0_608:
	global_load_dword v4, v2, s[14:15] sc1
	s_add_i32 s2, s2, 1
	s_mov_b64 s[22:23], -1
	s_waitcnt vmcnt(0)
	v_cmp_ge_u32_e32 vcc, v4, v3
	s_orn2_b64 s[20:21], vcc, exec
	s_branch .LBB0_603

.LBB0_617:
	s_or_b64 exec, exec, s[10:11]
	v_cvt_f32_u32_e32 v5, v2
	s_waitcnt vmcnt(0)
	v_readfirstlane_b32 s2, v4
	s_add_u32 s10, s88, 0xc680400
	s_addc_u32 s11, s89, 0
	v_rcp_iflag_f32_e32 v5, v5
	v_add_u32_e32 v3, s2, v3
	v_add_u32_e32 v6, 1, v3
	s_mov_b64 s[12:13], 0
	v_mul_f32_e32 v4, 0x4f7ffffe, v5
	v_cvt_u32_f32_e32 v4, v4
	v_sub_u32_e32 v5, 0, v2
	v_mul_lo_u32 v5, v5, v4
	v_mul_hi_u32 v5, v4, v5
	v_add_u32_e32 v4, v4, v5
	v_mul_hi_u32 v4, v3, v4
	v_mul_lo_u32 v5, v4, v2
	v_sub_u32_e32 v3, v3, v5
	v_add_u32_e32 v7, 1, v4
	v_cmp_ge_u32_e32 vcc, v3, v2
	v_sub_u32_e32 v5, v3, v2
	s_nop 0
	v_cndmask_b32_e32 v4, v4, v7, vcc
	v_cndmask_b32_e32 v3, v3, v5, vcc
	v_add_u32_e32 v5, 1, v4
	v_cmp_ge_u32_e32 vcc, v3, v2
	s_nop 1
	v_cndmask_b32_e32 v4, v4, v5, vcc
	v_mul_lo_u32 v3, v2, v4
	v_add_u32_e32 v2, v3, v2
	v_cmp_ne_u32_e32 vcc, v6, v2
	v_mov_b32_e32 v4, v2
	v_mov_b64_e32 v[2:3], s[10:11]
	s_and_saveexec_b64 s[8:9], vcc
	s_cbranch_execz .LBB0_629
	v_mov_b32_e32 v2, 0
	global_load_dword v3, v2, s[10:11] sc1
	s_mov_b64 s[16:17], 0
	s_waitcnt vmcnt(0)
	v_cmp_lt_u32_e32 vcc, v3, v4
	s_and_saveexec_b64 s[14:15], vcc
	s_cbranch_execz .LBB0_628
	s_add_u32 s12, s88, 0xc67d200
	s_addc_u32 s13, s89, 0
	s_mov_b32 s2, 1
	s_branch .LBB0_621

.LBB0_625:
	global_load_dword v3, v2, s[10:11] sc1
	s_add_i32 s2, s2, 1
	s_mov_b64 s[20:21], -1
	s_waitcnt vmcnt(0)
	v_cmp_ge_u32_e32 vcc, v3, v4
	s_orn2_b64 s[24:25], vcc, exec
	s_branch .LBB0_620

.LBB0_660:
	s_or_b64 exec, exec, s[8:9]
	buffer_inv sc1
	v_cvt_f32_u32_e32 v6, v4
	s_waitcnt vmcnt(1)
	v_readfirstlane_b32 s2, v5
	v_sub_u32_e32 v5, 0, v4
	v_rcp_iflag_f32_e32 v6, v6
	v_add_u32_e32 v7, s2, v3
	v_mul_f32_e32 v6, 0x4f7ffffe, v6
	v_cvt_u32_f32_e32 v6, v6
	v_mul_lo_u32 v3, v5, v6
	v_mul_hi_u32 v3, v6, v3
	v_add_u32_e32 v3, v6, v3
	v_mul_hi_u32 v3, v7, v3
	v_mul_lo_u32 v5, v3, v4
	v_sub_u32_e32 v5, v7, v5
	v_add_u32_e32 v6, 1, v3
	v_cmp_ge_u32_e32 vcc, v5, v4
	s_nop 1
	v_cndmask_b32_e32 v3, v3, v6, vcc
	v_sub_u32_e32 v6, v5, v4
	v_cndmask_b32_e32 v5, v5, v6, vcc
	v_add_u32_e32 v6, 1, v3
	v_cmp_ge_u32_e32 vcc, v5, v4
	v_add_u32_e32 v5, 1, v7
	s_nop 0
	v_cndmask_b32_e32 v3, v3, v6, vcc
	v_mul_lo_u32 v6, v4, v3
	v_add_u32_e32 v4, v6, v4
	v_cmp_ne_u32_e32 vcc, v5, v4
	s_and_saveexec_b64 s[2:3], vcc
	s_xor_b64 s[6:7], exec, s[2:3]
	s_cbranch_execz .LBB0_674
	s_waitcnt lgkmcnt(0)
	v_add_u32_e32 v3, 1, v3
	v_mul_lo_u32 v3, v3, v2
	v_mov_b32_e32 v2, 0x3400
	global_load_dword v2, v2, s[60:61] sc1
	s_add_u32 s12, s60, 0x3400
	s_addc_u32 s13, s61, 0
	s_waitcnt vmcnt(0)
	v_cmp_lt_u32_e32 vcc, v2, v3
	s_and_saveexec_b64 s[8:9], vcc
	s_cbranch_execz .LBB0_673
	s_add_u32 s10, s88, 0xc67d200
	s_addc_u32 s11, s89, 0
	s_mov_b32 s2, 1
	s_mov_b64 s[14:15], 0
	v_mov_b32_e32 v2, 0
	s_branch .LBB0_664

.LBB0_668:
	global_load_dword v4, v2, s[12:13] sc1
	s_add_i32 s2, s2, 1
	s_mov_b64 s[20:21], -1
	s_waitcnt vmcnt(0)
	v_cmp_ge_u32_e32 vcc, v4, v3
	s_orn2_b64 s[18:19], vcc, exec
	s_branch .LBB0_663

.LBB0_677:
	s_or_b64 exec, exec, s[8:9]
	v_cvt_f32_u32_e32 v5, v2
	s_waitcnt vmcnt(0)
	v_readfirstlane_b32 s2, v4
	s_add_u32 s8, s88, 0xc680400
	s_addc_u32 s9, s89, 0
	v_rcp_iflag_f32_e32 v5, v5
	v_add_u32_e32 v3, s2, v3
	v_add_u32_e32 v6, 1, v3
	s_mov_b64 s[10:11], 0
	v_mul_f32_e32 v4, 0x4f7ffffe, v5
	v_cvt_u32_f32_e32 v4, v4
	v_sub_u32_e32 v5, 0, v2
	v_mul_lo_u32 v5, v5, v4
	v_mul_hi_u32 v5, v4, v5
	v_add_u32_e32 v4, v4, v5
	v_mul_hi_u32 v4, v3, v4
	v_mul_lo_u32 v5, v4, v2
	v_sub_u32_e32 v3, v3, v5
	v_add_u32_e32 v7, 1, v4
	v_cmp_ge_u32_e32 vcc, v3, v2
	v_sub_u32_e32 v5, v3, v2
	s_nop 0
	v_cndmask_b32_e32 v4, v4, v7, vcc
	v_cndmask_b32_e32 v3, v3, v5, vcc
	v_add_u32_e32 v5, 1, v4
	v_cmp_ge_u32_e32 vcc, v3, v2
	s_nop 1
	v_cndmask_b32_e32 v4, v4, v5, vcc
	v_mul_lo_u32 v3, v2, v4
	v_add_u32_e32 v2, v3, v2
	v_cmp_ne_u32_e32 vcc, v6, v2
	v_mov_b32_e32 v4, v2
	v_mov_b64_e32 v[2:3], s[8:9]
	s_and_saveexec_b64 s[6:7], vcc
	s_cbranch_execz .LBB0_689
	v_mov_b32_e32 v2, 0
	global_load_dword v3, v2, s[8:9] sc1
	s_mov_b64 s[14:15], 0
	s_waitcnt vmcnt(0)
	v_cmp_lt_u32_e32 vcc, v3, v4
	s_and_saveexec_b64 s[12:13], vcc
	s_cbranch_execz .LBB0_688
	s_add_u32 s10, s88, 0xc67d200
	s_addc_u32 s11, s89, 0
	s_mov_b32 s2, 1
	s_branch .LBB0_681

.LBB0_685:
	global_load_dword v3, v2, s[8:9] sc1
	s_add_i32 s2, s2, 1
	s_mov_b64 s[18:19], -1
	s_waitcnt vmcnt(0)
	v_cmp_ge_u32_e32 vcc, v3, v4
	s_orn2_b64 s[22:23], vcc, exec
	s_branch .LBB0_680

.LBB0_742:
	s_or_b64 exec, exec, s[12:13]
	buffer_inv sc1
	v_cvt_f32_u32_e32 v6, v4
	s_waitcnt vmcnt(1)
	v_readfirstlane_b32 s2, v5
	v_sub_u32_e32 v5, 0, v4
	v_rcp_iflag_f32_e32 v6, v6
	v_add_u32_e32 v7, s2, v3
	v_mul_f32_e32 v6, 0x4f7ffffe, v6
	v_cvt_u32_f32_e32 v6, v6
	v_mul_lo_u32 v3, v5, v6
	v_mul_hi_u32 v3, v6, v3
	v_add_u32_e32 v3, v6, v3
	v_mul_hi_u32 v3, v7, v3
	v_mul_lo_u32 v5, v3, v4
	v_sub_u32_e32 v5, v7, v5
	v_add_u32_e32 v6, 1, v3
	v_cmp_ge_u32_e32 vcc, v5, v4
	s_nop 1
	v_cndmask_b32_e32 v3, v3, v6, vcc
	v_sub_u32_e32 v6, v5, v4
	v_cndmask_b32_e32 v5, v5, v6, vcc
	v_add_u32_e32 v6, 1, v3
	v_cmp_ge_u32_e32 vcc, v5, v4
	v_add_u32_e32 v5, 1, v7
	s_nop 0
	v_cndmask_b32_e32 v3, v3, v6, vcc
	v_mul_lo_u32 v6, v4, v3
	v_add_u32_e32 v4, v6, v4
	v_cmp_ne_u32_e32 vcc, v5, v4
	s_and_saveexec_b64 s[2:3], vcc
	s_xor_b64 s[10:11], exec, s[2:3]
	s_cbranch_execz .LBB0_756
	s_waitcnt lgkmcnt(0)
	v_add_u32_e32 v3, 1, v3
	v_mul_lo_u32 v3, v3, v2
	v_mov_b32_e32 v2, 0x3400
	global_load_dword v2, v2, s[60:61] sc1
	s_add_u32 s16, s60, 0x3400
	s_addc_u32 s17, s61, 0
	s_waitcnt vmcnt(0)
	v_cmp_lt_u32_e32 vcc, v2, v3
	s_and_saveexec_b64 s[12:13], vcc
	s_cbranch_execz .LBB0_755
	s_add_u32 s14, s88, 0xc67d200
	s_addc_u32 s15, s89, 0
	s_mov_b32 s2, 1
	s_mov_b64 s[18:19], 0
	v_mov_b32_e32 v2, 0
	s_branch .LBB0_746

.LBB0_750:
	global_load_dword v4, v2, s[16:17] sc1
	s_add_i32 s2, s2, 1
	s_mov_b64 s[28:29], -1
	s_waitcnt vmcnt(0)
	v_cmp_ge_u32_e32 vcc, v4, v3
	s_orn2_b64 s[22:23], vcc, exec
	s_branch .LBB0_745

.LBB0_759:
	s_or_b64 exec, exec, s[12:13]
	v_cvt_f32_u32_e32 v5, v2
	s_waitcnt vmcnt(0)
	v_readfirstlane_b32 s2, v4
	s_add_u32 s12, s88, 0xc680400
	s_addc_u32 s13, s89, 0
	v_rcp_iflag_f32_e32 v5, v5
	v_add_u32_e32 v3, s2, v3
	v_add_u32_e32 v6, 1, v3
	s_mov_b64 s[14:15], 0
	v_mul_f32_e32 v4, 0x4f7ffffe, v5
	v_cvt_u32_f32_e32 v4, v4
	v_sub_u32_e32 v5, 0, v2
	v_mul_lo_u32 v5, v5, v4
	v_mul_hi_u32 v5, v4, v5
	v_add_u32_e32 v4, v4, v5
	v_mul_hi_u32 v4, v3, v4
	v_mul_lo_u32 v5, v4, v2
	v_sub_u32_e32 v3, v3, v5
	v_add_u32_e32 v7, 1, v4
	v_cmp_ge_u32_e32 vcc, v3, v2
	v_sub_u32_e32 v5, v3, v2
	s_nop 0
	v_cndmask_b32_e32 v4, v4, v7, vcc
	v_cndmask_b32_e32 v3, v3, v5, vcc
	v_add_u32_e32 v5, 1, v4
	v_cmp_ge_u32_e32 vcc, v3, v2
	s_nop 1
	v_cndmask_b32_e32 v4, v4, v5, vcc
	v_mul_lo_u32 v3, v2, v4
	v_add_u32_e32 v2, v3, v2
	v_cmp_ne_u32_e32 vcc, v6, v2
	v_mov_b32_e32 v4, v2
	v_mov_b64_e32 v[2:3], s[12:13]
	s_and_saveexec_b64 s[10:11], vcc
	s_cbranch_execz .LBB0_771
	v_mov_b32_e32 v2, 0
	global_load_dword v3, v2, s[12:13] sc1
	s_mov_b64 s[18:19], 0
	s_waitcnt vmcnt(0)
	v_cmp_lt_u32_e32 vcc, v3, v4
	s_and_saveexec_b64 s[16:17], vcc
	s_cbranch_execz .LBB0_770
	s_add_u32 s14, s88, 0xc67d200
	s_addc_u32 s15, s89, 0
	s_mov_b32 s2, 1
	s_branch .LBB0_763

.LBB0_767:
	global_load_dword v3, v2, s[12:13] sc1
	s_add_i32 s2, s2, 1
	s_mov_b64 s[22:23], -1
	s_waitcnt vmcnt(0)
	v_cmp_ge_u32_e32 vcc, v3, v4
	s_orn2_b64 s[30:31], vcc, exec
	s_branch .LBB0_762

.LBB0_896:
	global_load_dword v3, v2, s[10:11] sc1
	s_add_i32 s2, s2, 1
	s_mov_b64 s[20:21], -1
	s_waitcnt vmcnt(0)
	v_cmp_ge_u32_e32 vcc, v3, v4
	s_orn2_b64 s[28:29], vcc, exec
	s_branch .LBB0_891
